# stack5 + QKV GEMM tile traversal in groups of 8 row tiles (rounds of 8x4 tiles, no group straddling) instead of 4
# baseline (speedup 1.0000x reference)
;     __host__ __device__ bool next(int i, Unit& u) const {
;         const long L = (long)i * G + c; if (L >= nwg) return false;
;         int wgid = (int)L; { const int q = nwg / NXCD, r = nwg % NXCD, xcd = wgid % NXCD, off = wgid / NXCD; wgid = (xcd < r ? xcd * (q + 1) : r * (q + 1) + (xcd - r) * q) + off; }
;         const int nig = WGM * nN, gid = wgid / nig, fm = gid * WGM, gsz = (nM - fm) < WGM ? (nM - fm) : WGM;
;         u.pm = fm + ((wgid % nig) % gsz); u.pn = (wgid % nig) / gsz; return true;
; template <class Epi, class Sched, bool ALIGN_EPI = false, bool SP2 = false>
; __device__ __forceinline__ void gemm_phase(PG8_LAS unsigned char* lds, const Gemm g, const Sched& S, const Epi& E, const int tid_in) {
;     int tid = tid_in; asm volatile("" : "+v"(tid)); const int wid = __builtin_amdgcn_readfirstlane(tid >> 6), lane = tid & 63, wr = wid >> 2, wc = wid & 3, fr = lane & 15, fq = lane >> 4;
;     const int K = g.K, nt = K / BK;
;     unsigned voffA[2], voffB[2];
; #pragma unroll
;     for (int i = 0; i < 2; ++i) { int R, C; stage_rc(tid * 16 + i * 8192, R, C); const int Rb = Epi::PERM ? ((R & ~31) + perm32(R & 31)) : R;
;         voffA[i] = (unsigned)(R * K + C) * 2u; voffB[i] = (unsigned)(Rb * K + C) * 2u; }
;     const size_t kstep = (size_t)(BK * 2);
;     const size_t hstep = (size_t)HALF * K * 2;
;     const size_t tstep = 2 * hstep;
;     const unsigned ldsw = (unsigned)wid * 1024u;
;     const int aoff = lds_byte(wr * 64 + fr, fq * 8), boff = lds_byte(wc * 32 + fr, fq * 8);
;     ...
;     Unit cur, nxt; int ui = 0;
;     if (!S.next(0, cur)) return;
.LBB0_81:
	s_mov_b64 s[2:3], s[84:85]
	s_mov_b32 s0, -1
	s_nop 0
	v_mbcnt_lo_u32_b32 v0, s0, 0
	v_mbcnt_hi_u32_b32 v0, s0, v0
	s_waitcnt vmcnt(0)
	v_or_b32_e32 v16, s83, v0
	s_mov_b32 s0, s82
	s_load_dwordx2 s[4:5], s[2:3], 0x90
	s_cmpk_lt_i32 s0, 0x600
	s_cselect_b64 s[6:7], -1, 0
	s_cmpk_gt_i32 s0, 0x5ff
	v_readfirstlane_b32 s8, v16
	s_cbranch_scc1 .LBB0_83
	s_ashr_i32 s1, s0, 31
	s_lshr_b32 s1, s1, 29
	s_add_i32 s1, s0, s1
	s_ashr_i32 s2, s1, 3
	s_and_b32 s1, s1, -8
	s_sub_i32 s1, s0, s1
	s_cmp_lt_i32 s1, 0
	s_cselect_b32 s3, s86, 0xc0
	s_mul_i32 s1, s1, s3
	s_add_i32 s1, s1, s2
	s_mul_hi_i32 s2, s1, 0x2aaaaaab
	s_lshr_b32 s3, s2, 31
	s_ashr_i32 s2, s2, 4
	s_add_i32 s2, s2, s3
	s_lshl_b32 s3, s2, 3
	s_mul_i32 s2, s2, 0x60
	s_sub_i32 s1, s1, s2
	s_bfe_i32 s2, s1, 0x80000
	s_bfe_u32 s2, s2, 0x3000d
	s_add_i32 s2, s1, s2
	s_bfe_i32 s9, s2, 0x80000
	s_and_b32 s2, s2, 0xf8
	s_sub_i32 s1, s1, s2
	s_sext_i32_i16 s9, s9
	s_sext_i32_i8 s1, s1
	s_add_i32 s10, s3, s1
	s_ashr_i32 s76, s9, 3

;     __host__ __device__ bool next(int i, Unit& u) const {
;         const long L = (long)i * G + c; if (L >= nwg) return false;
;         int wgid = (int)L; { const int q = nwg / NXCD, r = nwg % NXCD, xcd = wgid % NXCD, off = wgid / NXCD; wgid = (xcd < r ? xcd * (q + 1) : r * (q + 1) + (xcd - r) * q) + off; }
;         const int nig = WGM * nN, gid = wgid / nig, fm = gid * WGM, gsz = (nM - fm) < WGM ? (nM - fm) : WGM;
;         u.pm = fm + ((wgid % nig) % gsz); u.pn = (wgid % nig) / gsz; return true;
;     }
; __device__ __forceinline__ unsigned cvt_pk_bf16(float lo, float hi) { unsigned r; asm volatile("v_cvt_pk_bf16_f32 %0, %1, %2" : "=v"(r) : "v"(lo), "v"(hi)); return r; }
;     __device__ __forceinline__ void pre(const Unit& u, int wr, int fr, float (&rsv)[8]) const {
; #pragma unroll
;         for (int i = 0; i < 8; ++i) rsv[i] = rs[u.pm * BM + wr * 64 + fr + (i >> 2) * HALF + (i & 3) * 16]; }
; template <class Epi, class Sched, bool ALIGN_EPI = false, bool SP2 = false>
; __device__ __forceinline__ void gemm_phase(PG8_LAS unsigned char* lds, const Gemm g, const Sched& S, const Epi& E, const int tid_in) {
;     ...
;         float rsv[8]; E.pre(cur, wr, fr, rsv);
;         const bool has_next = S.next(ui + 1, nxt);
.LBB0_89:
	v_lshl_add_u32 v160, s10, 8, v170
	v_ashrrev_i32_e32 v161, 31, v160
	v_lshl_add_u64 v[2:3], v[160:161], 2, s[18:19]
	global_load_dword v182, v[2:3], off
	global_load_dword v181, v[2:3], off offset:64
	global_load_dword v180, v[2:3], off offset:128
	global_load_dword v179, v[2:3], off offset:192
	global_load_dword v178, v[2:3], off offset:512
	global_load_dword v177, v[2:3], off offset:576
	global_load_dword v176, v[2:3], off offset:640
	global_load_dword v175, v[2:3], off offset:704
	s_add_i32 s37, s37, 1
	s_mul_i32 s4, s37, s25
	s_mul_hi_u32 s5, s37, s24
	s_add_i32 s5, s5, s4
	s_mul_i32 s4, s37, s24
	s_add_u32 s72, s4, s0
	s_addc_u32 s73, s5, s38
	v_mov_b64_e32 v[2:3], 0x600
	v_cmp_gt_i64_e32 vcc, s[72:73], v[236:237]
	v_cmp_lt_i64_e64 s[4:5], s[72:73], v[2:3]
	s_cbranch_vccnz .LBB0_91
	s_ashr_i32 s10, s72, 31
	s_lshr_b32 s10, s10, 29
	s_add_i32 s10, s72, s10
	s_ashr_i32 s11, s10, 3
	s_and_b32 s10, s10, -8
	s_sub_i32 s10, s72, s10
	s_cmp_lt_i32 s10, 0
	s_cselect_b32 s42, s86, 0xc0
	s_mul_i32 s10, s10, s42
	s_add_i32 s10, s10, s11
	s_mul_hi_i32 s11, s10, 0x2aaaaaab
	s_lshr_b32 s42, s11, 31
	s_ashr_i32 s11, s11, 4
	s_add_i32 s11, s11, s42
	s_lshl_b32 s42, s11, 3
	s_sub_i32 s43, 0x80, s42
	s_min_i32 s43, s43, 8
	s_abs_i32 s58, s43
	v_cvt_f32_u32_e32 v2, s58
	s_sub_i32 s60, 0, s58
	s_mul_i32 s11, s11, 0x60
	s_sub_i32 s10, s10, s11
	v_rcp_iflag_f32_e32 v2, v2
	s_abs_i32 s11, s10
	s_xor_b32 s59, s10, s43
	s_ashr_i32 s59, s59, 31
	v_mul_f32_e32 v2, 0x4f7ffffe, v2
	v_cvt_u32_f32_e32 v2, v2
	s_nop 0
	v_readfirstlane_b32 s61, v2
	s_mul_i32 s60, s60, s61
	s_mul_hi_u32 s60, s61, s60
	s_add_i32 s61, s61, s60
	s_mul_hi_u32 s60, s11, s61
	s_mul_i32 s61, s60, s58
	s_sub_i32 s11, s11, s61
	s_add_i32 s62, s60, 1
	s_sub_i32 s61, s11, s58
	s_cmp_ge_u32 s11, s58
	s_cselect_b32 s60, s62, s60
	s_cselect_b32 s11, s61, s11
	s_add_i32 s61, s60, 1
	s_cmp_ge_u32 s11, s58
	s_cselect_b32 s11, s61, s60
	s_xor_b32 s11, s11, s59
	s_sub_i32 s70, s11, s59
	s_mul_i32 s11, s70, s43
	s_sub_i32 s10, s10, s11
	s_add_i32 s10, s42, s10
